# f1 + SSD operand-relayout section: one lgkmcnt wait per weight-quad read pair instead of a drain in front of every guarded ds_write
# speedup vs baseline: 1.0017x; 1.0017x over previous
; #define LAS __attribute__((address_space(3)))
; #define LDS_BARRIER() asm volatile("s_waitcnt lgkmcnt(0)\n\ts_barrier" ::: "memory")
; __device__ __forceinline__ void ssd_item(LAS unsigned char* lds, int b, int hh, const Args& a) {
;     ...
;         LDS_BARRIER();
;         const float acl = acum[127];
;         if (cact) {
;             LAS unsigned char* rm = lds + (role == 2 ? O_CM : O_BM);
;             LAS unsigned char* tr = lds + (role == 0 ? O_XT : O_BWT);
;     ...
;             SSD_CONV8(inA, sg);
;             SSD_CONV8(inB, sg + 6);
;             if (three) SSD_CONV8(inC, sg + 12);
.LBB0_859:
	s_waitcnt lgkmcnt(0)
	s_barrier
	v_mov_b32_e32 v18, s84
	ds_read_b32 v59, v18
	s_and_saveexec_b64 s[62:63], s[2:3]
	s_cbranch_execz .LBB0_913
	ds_read_b128 v[22:25], v137
	ds_read_b128 v[18:21], v137 offset:16
	s_waitcnt lgkmcnt(0)
	v_mov_b32_e32 v26, 1.0
	v_mov_b32_e32 v27, 1.0
	s_and_saveexec_b64 s[64:65], s[12:13]
	s_cbranch_execz .LBB0_862
	v_cndmask_b32_e64 v27, 1.0, v22, s[10:11]
	ds_write_b64 v157, v[64:65]
.LBB0_862:
	s_or_b64 exec, exec, s[64:65]
	s_and_saveexec_b64 s[64:65], s[12:13]
	s_cbranch_execz .LBB0_864
	v_cndmask_b32_e64 v26, 1.0, v23, s[10:11]
	ds_write_b64 v157, v[68:69] offset:272
.LBB0_864:
	s_or_b64 exec, exec, s[64:65]
	v_mov_b32_e32 v22, 1.0
	v_mov_b32_e32 v23, 1.0
	s_and_saveexec_b64 s[64:65], s[12:13]
	v_cndmask_b32_e64 v23, 1.0, v24, s[10:11]
	ds_write_b64 v157, v[74:75] offset:544
	s_or_b64 exec, exec, s[64:65]
	s_and_saveexec_b64 s[64:65], s[12:13]
	v_cndmask_b32_e64 v22, 1.0, v25, s[10:11]
	ds_write_b64 v157, v[80:81] offset:816
	s_or_b64 exec, exec, s[64:65]
	v_mov_b32_e32 v24, 1.0
	v_mov_b32_e32 v25, 1.0
	s_and_saveexec_b64 s[64:65], s[12:13]
	s_cbranch_execz .LBB0_870
	v_cndmask_b32_e64 v25, 1.0, v18, s[10:11]
	ds_write_b64 v157, v[86:87] offset:1088
.LBB0_870:
	s_or_b64 exec, exec, s[64:65]
	s_and_saveexec_b64 s[64:65], s[12:13]
	s_cbranch_execz .LBB0_872
	v_cndmask_b32_e64 v24, 1.0, v19, s[10:11]
	ds_write_b64 v157, v[106:107] offset:1360
.LBB0_872:
	s_or_b64 exec, exec, s[64:65]
	v_mov_b32_e32 v18, 1.0
	v_mov_b32_e32 v19, 1.0
	s_and_saveexec_b64 s[64:65], s[12:13]
	s_cbranch_execnz .LBB0_892
	s_or_b64 exec, exec, s[64:65]
	s_and_saveexec_b64 s[64:65], s[12:13]
	s_cbranch_execnz .LBB0_893

; __device__ __forceinline__ void ssd_item(LAS unsigned char* lds, int b, int hh, const Args& a) {
;     ...
;             SSD_CONV8(inA, sg);
;             SSD_CONV8(inB, sg + 6);
.LBB0_876:
	s_or_b64 exec, exec, s[64:65]
	ds_read_b128 v[22:25], v148
	ds_read_b128 v[18:21], v148 offset:16
	s_waitcnt lgkmcnt(0)
	v_mov_b32_e32 v26, 1.0
	v_mov_b32_e32 v27, 1.0
	s_and_saveexec_b64 s[64:65], s[12:13]
	s_cbranch_execz .LBB0_878
	v_cndmask_b32_e64 v27, 1.0, v22, s[10:11]
	ds_write_b64 v157, v[66:67] offset:13056
.LBB0_878:
	s_or_b64 exec, exec, s[64:65]
	s_and_saveexec_b64 s[64:65], s[12:13]
	s_cbranch_execz .LBB0_880
	v_cndmask_b32_e64 v26, 1.0, v23, s[10:11]
	ds_write_b64 v157, v[70:71] offset:13328
.LBB0_880:
	s_or_b64 exec, exec, s[64:65]
	v_mov_b32_e32 v22, 1.0
	v_mov_b32_e32 v23, 1.0
	s_and_saveexec_b64 s[64:65], s[12:13]
	v_cndmask_b32_e64 v23, 1.0, v24, s[10:11]
	ds_write_b64 v157, v[76:77] offset:13600
	s_or_b64 exec, exec, s[64:65]
	s_and_saveexec_b64 s[64:65], s[12:13]
	v_cndmask_b32_e64 v22, 1.0, v25, s[10:11]
	ds_write_b64 v157, v[82:83] offset:13872
	s_or_b64 exec, exec, s[64:65]
	v_mov_b32_e32 v24, 1.0
	v_mov_b32_e32 v25, 1.0
	s_and_saveexec_b64 s[64:65], s[12:13]
	s_cbranch_execz .LBB0_886
	v_cndmask_b32_e64 v25, 1.0, v18, s[10:11]
	ds_write_b64 v157, v[88:89] offset:14144
.LBB0_886:
	s_or_b64 exec, exec, s[64:65]
	s_and_saveexec_b64 s[64:65], s[12:13]
	s_cbranch_execz .LBB0_888
	v_cndmask_b32_e64 v24, 1.0, v19, s[10:11]
	ds_write_b64 v157, v[108:109] offset:14416

; __device__ __forceinline__ void ssd_item(LAS unsigned char* lds, int b, int hh, const Args& a) {
;     ...
;             SSD_CONV8(inA, sg);
;             SSD_CONV8(inB, sg + 6);
;             if (three) SSD_CONV8(inC, sg + 12);
.LBB0_897:
	ds_read_b128 v[22:25], v150
	ds_read_b128 v[18:21], v150 offset:16
	s_waitcnt lgkmcnt(0)
	v_mov_b32_e32 v26, 1.0
	v_mov_b32_e32 v27, 1.0
	s_and_saveexec_b64 s[64:65], s[12:13]
	s_cbranch_execz .LBB0_899
	v_cndmask_b32_e64 v27, 1.0, v22, s[10:11]
	ds_write_b64 v157, v[62:63] offset:26112
.LBB0_899:
	s_or_b64 exec, exec, s[64:65]
	s_and_saveexec_b64 s[64:65], s[12:13]
	s_cbranch_execz .LBB0_901
	v_cndmask_b32_e64 v26, 1.0, v23, s[10:11]
	ds_write_b64 v157, v[72:73] offset:26384
.LBB0_901:
	s_or_b64 exec, exec, s[64:65]
	v_mov_b32_e32 v22, 1.0
	v_mov_b32_e32 v23, 1.0
	s_and_saveexec_b64 s[64:65], s[12:13]
	v_cndmask_b32_e64 v23, 1.0, v24, s[10:11]
	ds_write_b64 v157, v[78:79] offset:26656
	s_or_b64 exec, exec, s[64:65]
	s_and_saveexec_b64 s[64:65], s[12:13]
	v_cndmask_b32_e64 v22, 1.0, v25, s[10:11]
	ds_write_b64 v157, v[84:85] offset:26928
	s_or_b64 exec, exec, s[64:65]
	v_mov_b32_e32 v24, 1.0
	v_mov_b32_e32 v25, 1.0
	s_and_saveexec_b64 s[64:65], s[12:13]
	s_cbranch_execz .LBB0_907
	v_cndmask_b32_e64 v25, 1.0, v18, s[10:11]
	ds_write_b64 v157, v[100:101] offset:27200
.LBB0_907:
	s_or_b64 exec, exec, s[64:65]
	s_and_saveexec_b64 s[64:65], s[12:13]
	s_cbranch_execz .LBB0_909
	v_cndmask_b32_e64 v24, 1.0, v19, s[10:11]
	ds_write_b64 v157, v[110:111] offset:27472
